# combo8 + E34: PG (residual + final RMSNorm) of slabs 0..2 moved out of every CU's path into the next slab's in-proj phase, run there by the 96 CUs that own 7 of 8 tile rounds, with a software-pipeline
# speedup vs baseline: 1.0608x; 1.0119x over previous
.LBB0_258:
	s_nop 0
	v_readlane_b32 s0, v255, 3
	v_readlane_b32 s1, v255, 4
	s_and_b64 vcc, exec, s[0:1]
	s_cbranch_vccz .LBB0_263
	v_mov_b32_e32 v0, v167
	v_readlane_b32 s1, v251, 14
	v_readfirstlane_b32 s0, v0
	s_ashr_i32 s0, s0, 6
	s_add_i32 s0, s0, s1
	s_cmpk_gt_i32 s0, 0x1fff
	s_cbranch_scc1 .LBB0_262
	v_readlane_b32 s10, v254, 62
	s_cmpk_lg_u32 s36, 0x100
	s_cbranch_scc1 .Ldpg_keep
	s_cmp_lt_u32 s10, 3
	s_cbranch_scc1 .LBB0_262
.Ldpg_keep:
	v_readlane_b32 s11, v254, 63
	s_mov_b32 s14, s10
	s_mulk_i32 s10, 0xc00
	s_ashr_i32 s11, s10, 31
	s_lshl_b64 s[10:11], s[10:11], 2
	s_add_u32 s12, s4, s10
	v_and_b32_e32 v2, 63, v0
	s_addc_u32 s13, s5, s11
	v_lshlrev_b32_e32 v0, 4, v2
	s_waitcnt lgkmcnt(0)
	v_mov_b32_e32 v1, v157
	v_lshlrev_b32_e32 v156, 3, v2
	v_lshl_add_u64 v[2:3], s[12:13], 0, v[0:1]
	s_mov_b64 s[12:13], 0x2a12000
	v_cmp_lt_i32_e32 vcc, v188, v187
	s_waitcnt vmcnt(0)
	v_lshl_add_u64 v[8:9], v[2:3], 0, s[12:13]
	s_mov_b32 s10, s14
	v_cndmask_b32_e32 v2, v185, v188, vcc
	v_cmp_lt_i32_e32 vcc, v189, v187
	v_lshlrev_b32_e32 v44, 2, v2
	v_writelane_b32 v254, s10, 62
	v_cndmask_b32_e32 v2, v185, v189, vcc
	v_cmp_lt_i32_e32 vcc, v190, v187
	v_lshlrev_b32_e32 v45, 2, v2
	s_ashr_i32 s15, s14, 31
	v_cndmask_b32_e32 v2, v185, v190, vcc
	v_cmp_lt_i32_e32 vcc, v191, v187
	v_writelane_b32 v254, s11, 63
	v_lshlrev_b32_e32 v46, 2, v2
	v_cndmask_b32_e32 v2, v185, v191, vcc
	v_cmp_lt_i32_e32 vcc, v250, v187
	s_lshl_b64 s[10:11], s[14:15], 23
	v_readlane_b32 s84, v254, 4
	v_lshlrev_b32_e32 v47, 2, v2
	v_cndmask_b32_e32 v2, v185, v250, vcc
	v_cmp_lt_i32_e32 vcc, v184, v187
	v_readlane_b32 s12, v251, 0
	v_readlane_b32 s85, v254, 5
	v_lshlrev_b32_e32 v48, 2, v2
	v_cndmask_b32_e32 v2, v185, v184, vcc
	v_readlane_b32 s16, v251, 4
	v_readlane_b32 s17, v251, 5
	v_readlane_b32 s18, v251, 6
	v_readlane_b32 s19, v251, 7
	v_lshl_add_u64 v[4:5], s[84:85], 0, v[0:1]
	v_lshl_add_u64 v[6:7], s[82:83], 0, v[156:157]
	v_lshlrev_b32_e32 v49, 2, v2
	v_lshl_add_u64 v[10:11], s[16:17], 0, v[0:1]
	v_lshl_add_u64 v[12:13], s[18:19], 0, v[156:157]
	v_readlane_b32 s86, v254, 6
	v_readlane_b32 s87, v254, 7
	v_readlane_b32 s88, v254, 8
	v_readlane_b32 s89, v254, 9
	v_readlane_b32 s90, v254, 10
	v_readlane_b32 s91, v254, 11
	v_readlane_b32 s92, v254, 12
	v_readlane_b32 s93, v254, 13
	v_readlane_b32 s94, v254, 14
	v_readlane_b32 s95, v254, 15
	v_readlane_b32 s96, v254, 16
	v_readlane_b32 s97, v254, 17
	v_readlane_b32 s98, v254, 18
	v_readlane_b32 s99, v254, 19
	v_readlane_b32 s13, v251, 1
	v_readlane_b32 s14, v251, 2
	v_readlane_b32 s15, v251, 3

.LBB0_418:
	s_cmpk_lg_u32 s36, 0x100
	s_cbranch_scc1 .Ldpg_skip
	s_cmpk_lt_u32 s57, 0xa0
	s_cbranch_scc1 .Ldpg_skip
	v_readlane_b32 s10, v254, 62
	s_nop 3
	s_cmp_eq_u32 s10, 0
	s_cbranch_scc1 .Ldpg_skip
	v_mov_b32_e32 v0, v167
	v_readlane_b32 s1, v251, 14
	v_readfirstlane_b32 s0, v0
	s_ashr_i32 s0, s0, 6
	s_add_i32 s0, s0, s1
	s_add_i32 s0, s0, 0xfffffb00
	s_mov_b32 s56, 0x800000
	v_readlane_b32 s10, v254, 62
	s_add_i32 s10, s10, -1
	v_readlane_b32 s11, v254, 63
	s_mov_b32 s14, s10
	s_mulk_i32 s10, 0xc00
	s_ashr_i32 s11, s10, 31
	s_lshl_b64 s[10:11], s[10:11], 2
	s_add_u32 s12, s4, s10
	v_and_b32_e32 v2, 63, v0
	s_addc_u32 s13, s5, s11
	v_lshlrev_b32_e32 v0, 4, v2
	s_waitcnt lgkmcnt(0)
	v_mov_b32_e32 v1, v157
	v_lshlrev_b32_e32 v156, 3, v2
	v_lshl_add_u64 v[2:3], s[12:13], 0, v[0:1]
	s_mov_b64 s[12:13], 0x2a12000
	v_cmp_lt_i32_e32 vcc, v188, v187
	s_waitcnt vmcnt(0)
	v_lshl_add_u64 v[8:9], v[2:3], 0, s[12:13]
	s_mov_b32 s10, s14
	v_cndmask_b32_e32 v2, v185, v188, vcc
	v_cmp_lt_i32_e32 vcc, v189, v187
	v_lshlrev_b32_e32 v44, 2, v2
	v_cndmask_b32_e32 v2, v185, v189, vcc
	v_cmp_lt_i32_e32 vcc, v190, v187
	v_lshlrev_b32_e32 v45, 2, v2
	s_ashr_i32 s15, s14, 31
	v_cndmask_b32_e32 v2, v185, v190, vcc
	v_cmp_lt_i32_e32 vcc, v191, v187
	v_lshlrev_b32_e32 v46, 2, v2
	v_cndmask_b32_e32 v2, v185, v191, vcc
	v_cmp_lt_i32_e32 vcc, v250, v187
	s_lshl_b64 s[10:11], s[14:15], 23
	v_readlane_b32 s84, v254, 4
	v_lshlrev_b32_e32 v47, 2, v2
	v_cndmask_b32_e32 v2, v185, v250, vcc
	v_cmp_lt_i32_e32 vcc, v184, v187
	v_readlane_b32 s12, v251, 0
	v_readlane_b32 s85, v254, 5
	v_lshlrev_b32_e32 v48, 2, v2
	v_cndmask_b32_e32 v2, v185, v184, vcc
	v_readlane_b32 s16, v251, 4
	v_readlane_b32 s17, v251, 5
	v_readlane_b32 s18, v251, 6
	v_readlane_b32 s19, v251, 7
	v_lshl_add_u64 v[4:5], s[84:85], 0, v[0:1]
	v_lshl_add_u64 v[6:7], s[82:83], 0, v[156:157]
	v_lshlrev_b32_e32 v49, 2, v2
	v_lshl_add_u64 v[10:11], s[16:17], 0, v[0:1]
	v_lshl_add_u64 v[12:13], s[18:19], 0, v[156:157]
	v_readlane_b32 s86, v254, 6
	v_readlane_b32 s87, v254, 7
	v_readlane_b32 s88, v254, 8
	v_readlane_b32 s89, v254, 9
	v_readlane_b32 s90, v254, 10
	v_readlane_b32 s91, v254, 11
	v_readlane_b32 s92, v254, 12
	v_readlane_b32 s93, v254, 13
	v_readlane_b32 s94, v254, 14
	v_readlane_b32 s95, v254, 15
	v_readlane_b32 s96, v254, 16
	v_readlane_b32 s97, v254, 17
	v_readlane_b32 s98, v254, 18
	v_readlane_b32 s99, v254, 19
	v_readlane_b32 s13, v251, 1
	v_readlane_b32 s14, v251, 2
	v_readlane_b32 s15, v251, 3
	global_load_dwordx4 v[64:67], v[8:9], off
	global_load_dwordx4 v[68:71], v[8:9], off offset:1024
	global_load_dwordx4 v[72:75], v[8:9], off offset:2048
	global_load_dwordx4 v[76:79], v[8:9], off offset:3072
	global_load_dwordx4 v[80:83], v[10:11], off
	global_load_dwordx4 v[84:87], v[10:11], off offset:1024
	global_load_dwordx4 v[88:91], v[10:11], off offset:2048
	global_load_dwordx4 v[92:95], v[10:11], off offset:3072
	s_ashr_i32 s13, s0, 31
	s_mov_b32 s12, s0
	s_lshl_b64 s[14:15], s[12:13], 11
	s_lshl_b64 s[12:13], s[12:13], 10
	s_add_u32 s12, s12, s10
	s_addc_u32 s13, s13, s11
	s_lshl_b64 s[12:13], s[12:13], 2
	v_lshl_add_u64 v[40:41], v[4:5], 0, s[12:13]
	v_lshl_add_u64 v[42:43], v[12:13], 0, s[12:13]
	v_lshl_add_u64 v[2:3], v[6:7], 0, s[14:15]
	global_load_dwordx2 v[112:113], v[42:43], off
	global_load_dwordx2 v[114:115], v[42:43], off offset:512
	global_load_dwordx2 v[116:117], v[42:43], off offset:1024
	global_load_dwordx2 v[118:119], v[42:43], off offset:1536
	global_load_dwordx2 v[120:121], v[2:3], off
	global_load_dwordx2 v[122:123], v[2:3], off offset:512
	global_load_dwordx2 v[124:125], v[2:3], off offset:1024
	global_load_dwordx2 v[126:127], v[2:3], off offset:1536
	global_load_dwordx4 v[96:99], v[40:41], off
	global_load_dwordx4 v[100:103], v[40:41], off offset:1024
	global_load_dwordx4 v[104:107], v[40:41], off offset:2048
	global_load_dwordx4 v[108:111], v[40:41], off offset:3072
	s_waitcnt vmcnt(0)
.Ldpg_loop:
	s_ashr_i32 s13, s0, 31
	s_mov_b32 s12, s0
	s_lshl_b64 s[12:13], s[12:13], 10
	s_add_u32 s12, s12, s10
	s_addc_u32 s13, s13, s11
	s_lshl_b64 s[12:13], s[12:13], 2
	v_lshl_add_u64 v[14:15], v[12:13], 0, s[12:13]
	v_lshl_add_u64 v[14:15], v[14:15], 0, v[156:157]
	s_add_i32 s32, s0, 0x300
	s_cmpk_gt_i32 s32, 0x1fff
	s_cselect_b32 s2, s0, s32
	s_waitcnt vmcnt(4)
	v_mov_b32_e32 v16, v96
	v_mov_b32_e32 v17, v97
	v_mov_b32_e32 v18, v98
	v_mov_b32_e32 v19, v99
	v_mov_b32_e32 v20, v100
	v_mov_b32_e32 v21, v101
	v_mov_b32_e32 v22, v102
	v_mov_b32_e32 v23, v103
	v_mov_b32_e32 v24, v104
	v_mov_b32_e32 v25, v105
	v_mov_b32_e32 v26, v106
	v_mov_b32_e32 v27, v107
	v_mov_b32_e32 v28, v108
	v_mov_b32_e32 v29, v109
	v_mov_b32_e32 v30, v110
	v_mov_b32_e32 v31, v111
	v_mov_b32_e32 v32, v112
	v_mov_b32_e32 v33, v113
	v_mov_b32_e32 v34, v114
	v_mov_b32_e32 v35, v115
	v_mov_b32_e32 v36, v116
	v_mov_b32_e32 v37, v117
	v_mov_b32_e32 v38, v118
	v_mov_b32_e32 v39, v119
	v_mov_b32_e32 v50, v120
	v_mov_b32_e32 v51, v121
	v_mov_b32_e32 v52, v122
	v_mov_b32_e32 v53, v123
	v_mov_b32_e32 v54, v124
	v_mov_b32_e32 v55, v125
	v_mov_b32_e32 v56, v126
	v_mov_b32_e32 v57, v127
	s_ashr_i32 s13, s2, 31
	s_mov_b32 s12, s2
	s_lshl_b64 s[14:15], s[12:13], 11
	s_lshl_b64 s[12:13], s[12:13], 10
	s_add_u32 s12, s12, s10
	s_addc_u32 s13, s13, s11
	s_lshl_b64 s[12:13], s[12:13], 2
	v_lshl_add_u64 v[40:41], v[4:5], 0, s[12:13]
	v_lshl_add_u64 v[42:43], v[12:13], 0, s[12:13]
	v_lshl_add_u64 v[2:3], v[6:7], 0, s[14:15]
	global_load_dwordx2 v[112:113], v[42:43], off
	global_load_dwordx2 v[114:115], v[42:43], off offset:512
	global_load_dwordx2 v[116:117], v[42:43], off offset:1024
	global_load_dwordx2 v[118:119], v[42:43], off offset:1536
	global_load_dwordx2 v[120:121], v[2:3], off
	global_load_dwordx2 v[122:123], v[2:3], off offset:512
	global_load_dwordx2 v[124:125], v[2:3], off offset:1024
	global_load_dwordx2 v[126:127], v[2:3], off offset:1536
	global_load_dwordx4 v[96:99], v[40:41], off
	global_load_dwordx4 v[100:103], v[40:41], off offset:1024
	global_load_dwordx4 v[104:107], v[40:41], off offset:2048
	global_load_dwordx4 v[108:111], v[40:41], off offset:3072
	v_lshlrev_b32_e32 v144, 16, v32
	v_and_b32_e32 v145, 0xffff0000, v32
	v_lshlrev_b32_e32 v146, 16, v33
	v_and_b32_e32 v147, 0xffff0000, v33
	v_lshlrev_b32_e32 v148, 16, v50
	v_and_b32_e32 v149, 0xffff0000, v50
	v_lshlrev_b32_e32 v150, 16, v51
	v_and_b32_e32 v151, 0xffff0000, v51
	v_pk_add_f32 v[128:129], v[144:145], v[148:149]
	v_pk_add_f32 v[130:131], v[146:147], v[150:151]
	v_pk_fma_f32 v[16:17], v[64:65], v[128:129], v[16:17]
	v_pk_fma_f32 v[18:19], v[66:67], v[130:131], v[18:19]
	v_lshlrev_b32_e32 v144, 16, v34
	v_and_b32_e32 v145, 0xffff0000, v34
	v_lshlrev_b32_e32 v146, 16, v35
	v_and_b32_e32 v147, 0xffff0000, v35
	v_lshlrev_b32_e32 v148, 16, v52
	v_and_b32_e32 v149, 0xffff0000, v52
	v_lshlrev_b32_e32 v150, 16, v53
	v_and_b32_e32 v151, 0xffff0000, v53
	v_pk_add_f32 v[132:133], v[144:145], v[148:149]
	v_pk_add_f32 v[134:135], v[146:147], v[150:151]
	v_pk_fma_f32 v[20:21], v[68:69], v[132:133], v[20:21]
	v_pk_fma_f32 v[22:23], v[70:71], v[134:135], v[22:23]
	v_lshlrev_b32_e32 v144, 16, v36
	v_and_b32_e32 v145, 0xffff0000, v36
	v_lshlrev_b32_e32 v146, 16, v37
	v_and_b32_e32 v147, 0xffff0000, v37
	v_lshlrev_b32_e32 v148, 16, v54
	v_and_b32_e32 v149, 0xffff0000, v54
	v_lshlrev_b32_e32 v150, 16, v55
	v_and_b32_e32 v151, 0xffff0000, v55
	v_pk_add_f32 v[136:137], v[144:145], v[148:149]
	v_pk_add_f32 v[138:139], v[146:147], v[150:151]
	v_pk_fma_f32 v[24:25], v[72:73], v[136:137], v[24:25]
	v_pk_fma_f32 v[26:27], v[74:75], v[138:139], v[26:27]
	v_lshlrev_b32_e32 v144, 16, v38
	v_and_b32_e32 v145, 0xffff0000, v38
	v_lshlrev_b32_e32 v146, 16, v39
	v_and_b32_e32 v147, 0xffff0000, v39
	v_lshlrev_b32_e32 v148, 16, v56
	v_and_b32_e32 v149, 0xffff0000, v56
	v_lshlrev_b32_e32 v150, 16, v57
	v_and_b32_e32 v151, 0xffff0000, v57
	v_pk_add_f32 v[140:141], v[144:145], v[148:149]
	v_pk_add_f32 v[142:143], v[146:147], v[150:151]
	v_pk_fma_f32 v[28:29], v[76:77], v[140:141], v[28:29]
	v_pk_fma_f32 v[30:31], v[78:79], v[142:143], v[30:31]
	v_mov_b32_e32 v144, v16
	v_mov_b32_e32 v145, v20
	v_mov_b32_e32 v146, v17
	v_mov_b32_e32 v147, v21
	v_pk_mul_f32 v[146:147], v[146:147], v[146:147]
	v_pk_fma_f32 v[144:145], v[144:145], v[144:145], v[146:147]
	v_mov_b32_e32 v146, v18
	v_mov_b32_e32 v147, v22
	s_nop 0
	v_pk_fma_f32 v[144:145], v[146:147], v[146:147], v[144:145]
	v_mov_b32_e32 v146, v19
	v_mov_b32_e32 v147, v23
	s_nop 0
	v_pk_fma_f32 v[144:145], v[146:147], v[146:147], v[144:145]
	v_mov_b32_e32 v148, v24
	v_mov_b32_e32 v149, v28
	v_mov_b32_e32 v150, v25
	v_mov_b32_e32 v151, v29
	v_pk_mul_f32 v[150:151], v[150:151], v[150:151]
	v_pk_fma_f32 v[148:149], v[148:149], v[148:149], v[150:151]
	v_mov_b32_e32 v150, v26
	v_mov_b32_e32 v151, v30
	s_nop 0
	v_pk_fma_f32 v[148:149], v[150:151], v[150:151], v[148:149]
	v_mov_b32_e32 v150, v27
	v_mov_b32_e32 v151, v31
	s_nop 0
	v_pk_fma_f32 v[148:149], v[150:151], v[150:151], v[148:149]
	v_add_f32_e32 v152, v144, v145
	v_add_f32_e32 v152, v152, v148
	v_add_f32_e32 v152, v152, v149
	ds_bpermute_b32 v153, v44, v152
	s_waitcnt lgkmcnt(0)
	v_add_f32_e32 v152, v152, v153
	ds_bpermute_b32 v153, v45, v152
	s_waitcnt lgkmcnt(0)
	v_add_f32_e32 v152, v152, v153
	ds_bpermute_b32 v153, v46, v152
	s_waitcnt lgkmcnt(0)
	v_add_f32_e32 v152, v152, v153
	ds_bpermute_b32 v153, v47, v152
	s_waitcnt lgkmcnt(0)
	v_add_f32_e32 v152, v152, v153
	ds_bpermute_b32 v153, v48, v152
	s_waitcnt lgkmcnt(0)
	v_add_f32_e32 v152, v152, v153
	ds_bpermute_b32 v153, v49, v152
	s_waitcnt lgkmcnt(0)
	v_add_f32_e32 v152, v152, v153
	v_fmamk_f32 v152, v152, 0x3a800000, v182
	v_cmp_gt_f32_e32 vcc, s56, v152
	v_mul_f32_e32 v153, 0x4b800000, v152
	s_nop 0
	v_cndmask_b32_e32 v152, v152, v153, vcc
	v_rsq_f32_e32 v152, v152
	s_nop 0
	v_mul_f32_e32 v153, 0x45800000, v152
	v_cndmask_b32_e32 v152, v152, v153, vcc
	s_nop 0
	v_pk_mul_f32 v[144:145], v[16:17], v[152:153] op_sel_hi:[1,0]
	v_pk_mul_f32 v[146:147], v[18:19], v[152:153] op_sel_hi:[1,0]
	v_pk_mul_f32 v[128:129], v[80:81], v[144:145]
	v_pk_mul_f32 v[130:131], v[82:83], v[146:147]
	global_store_dwordx4 v[14:15], v[128:131], off
	v_pk_mul_f32 v[144:145], v[20:21], v[152:153] op_sel_hi:[1,0]
	v_pk_mul_f32 v[146:147], v[22:23], v[152:153] op_sel_hi:[1,0]
	v_pk_mul_f32 v[132:133], v[84:85], v[144:145]
	v_pk_mul_f32 v[134:135], v[86:87], v[146:147]
	global_store_dwordx4 v[14:15], v[132:135], off offset:1024
	v_pk_mul_f32 v[144:145], v[24:25], v[152:153] op_sel_hi:[1,0]
	v_pk_mul_f32 v[146:147], v[26:27], v[152:153] op_sel_hi:[1,0]
	v_pk_mul_f32 v[136:137], v[88:89], v[144:145]
	v_pk_mul_f32 v[138:139], v[90:91], v[146:147]
	global_store_dwordx4 v[14:15], v[136:139], off offset:2048
	v_pk_mul_f32 v[144:145], v[28:29], v[152:153] op_sel_hi:[1,0]
	v_pk_mul_f32 v[146:147], v[30:31], v[152:153] op_sel_hi:[1,0]
	v_pk_mul_f32 v[140:141], v[92:93], v[144:145]
	v_pk_mul_f32 v[142:143], v[94:95], v[146:147]
	global_store_dwordx4 v[14:15], v[140:143], off offset:3072
	s_mov_b32 s0, s32
	s_cmpk_gt_i32 s0, 0x1fff
	s_cbranch_scc0 .Ldpg_loop
